# also the last 32 w_down transposes moved to phase-3 light workgroups (160 WGs now)
# speedup vs baseline: 1.2146x; 1.0053x over previous
.LBB0_230:
	v_readlane_b32 s64, v209, 33
	v_readlane_b32 s62, v209, 35
	s_mov_b64 s[40:41], 0
	v_readlane_b32 s60, v209, 37
	v_readlane_b32 s65, v209, 34
	v_readlane_b32 s63, v209, 36
	v_readlane_b32 s61, v209, 38
	s_cmpk_eq_i32 s72, 0x200
	s_cbranch_scc0 .Lp3h_no
	s_sub_i32 s50, s60, 0x100
	s_cmpk_lt_u32 s50, 0xa0
	s_cbranch_scc0 .Lp3h_no
	s_add_i32 s50, s50, 0x168
	s_movk_i32 s51, 0x200
	s_movk_i32 s52, 0x207
	s_movk_i32 s53, 0x440
	s_movk_i32 s54, 0x1e8
	s_add_u32 s46, s12, 8
	s_addc_u32 s47, s13, 0
	s_branch .Ltramp_p0a

.Lp5_idle:
	s_cmpk_eq_i32 s72, 0x200
	s_cbranch_scc0 .Lp5_idle_none
	s_add_u32 s46, s12, 8
	s_addc_u32 s47, s13, 0
	s_add_i32 s50, s60, 0x128
	s_movk_i32 s51, 0x100
	s_movk_i32 s52, 0x627
	s_mov_b32 s53, 0
	s_mov_b32 s54, 0
	s_branch .Ltramp_p0b

.LBB0_361:
	s_cmpk_eq_i32 s72, 0x200
	s_cbranch_scc0 .Lp1h_no
	s_sub_i32 s50, s60, 0x1c0
	s_cmpk_lt_u32 s50, 0x40
	s_cbranch_scc0 .Lp1h_no
	s_add_i32 s50, s50, 0x1e8
	s_movk_i32 s51, 0x200
	s_movk_i32 s52, 0x227
	s_mov_b32 s53, 0
	s_mov_b32 s54, 0
	s_add_u32 s46, s12, 8
	s_addc_u32 s47, s13, 0
	s_branch .Lp0_head

.LBB0_362:
	s_andn2_b64 vcc, exec, s[40:41]
	s_cbranch_vccnz .Ltramp7a
	v_readlane_b32 s20, v209, 10
	v_readlane_b32 s21, v209, 11
	s_andn2_b64 vcc, exec, s[20:21]
	s_cbranch_vccnz .Ltramp7a
	s_add_u32 s46, s12, 8
	s_addc_u32 s47, s13, 0
	s_mov_b32 s50, s60
	s_mov_b32 s51, s72
	s_movk_i32 s52, 0xaf0
	s_mov_b32 s53, 0
	s_cmpk_eq_i32 s72, 0x200
	s_cbranch_scc0 .Lp0_head
	s_movk_i32 s52, 0x610
	s_movk_i32 s53, 0x4e0
	s_movk_i32 s54, 0x168
	s_branch .Lp0_head

.Lp0_head:
	s_mov_b32 s8, s50
	s_cmp_lt_i32 s50, s54
	s_cbranch_scc1 .LBB0_489
	s_add_i32 s8, s50, s53
